# GEMM epilogue row-norm factors: 8 loads in flight per new row panel instead of 8 dependent round trips; GDN step-2 scalar loads batched; first K/V tile loads issued before MoBA top-3 selection
# baseline (speedup 1.0000x reference)
; __device__ __forceinline__ float ssq_val(u64 v) { return (float)v * (1.f / 4294967296.f); }
;     __device__ __forceinline__ void operator()(const f32x4 (&acc)[2][2][4][2], const Unit& u, int wr, int wc, int fr, int fq, LAS f32x4* rsc, bool reuse) const {
;     ...
; #pragma unroll
;                 for (int ai = 0; ai < 2; ++ai)
; #pragma unroll
;                     for (int m = 0; m < 4; ++m) rs[ai][m] = ssqf ? ssqf[row0 + ai * HALF + m * 16] : ssq_val(ssq[row0 + ai * HALF + m * 16]);
.LBB0_564:
	s_and_b64 vcc, exec, s[0:1]
	s_cbranch_vccz .LBB0_642
	s_mov_b64 s[0:1], -1
	s_cmp_eq_u32 s74, s70
	v_ashrrev_i32_e32 v211, 31, v210
	s_cbranch_scc1 .LBB0_645
	s_cmp_lg_u64 s[64:65], 0
	s_cbranch_scc0 .Lrs1_u64
	v_lshl_add_u64 v[176:177], v[210:211], 2, s[64:65]
	flat_load_dword v2, v[176:177]
	flat_load_dword v137, v[176:177] offset:64
	flat_load_dword v138, v[176:177] offset:128
	flat_load_dword v139, v[176:177] offset:192
	flat_load_dword v140, v[176:177] offset:512
	flat_load_dword v141, v[176:177] offset:576
	flat_load_dword v142, v[176:177] offset:640
	flat_load_dword v135, v[176:177] offset:704
	s_waitcnt vmcnt(0) lgkmcnt(0)
	s_branch .LBB0_590
.Lrs1_u64:
	v_lshl_add_u64 v[176:177], v[210:211], 3, s[20:21]
	flat_load_dwordx2 v[160:161], v[176:177]
	flat_load_dwordx2 v[162:163], v[176:177] offset:128
	flat_load_dwordx2 v[164:165], v[176:177] offset:256
	flat_load_dwordx2 v[166:167], v[176:177] offset:384
	flat_load_dwordx2 v[168:169], v[176:177] offset:1024
	flat_load_dwordx2 v[170:171], v[176:177] offset:1152
	flat_load_dwordx2 v[172:173], v[176:177] offset:1280
	flat_load_dwordx2 v[174:175], v[176:177] offset:1408
	s_waitcnt vmcnt(0) lgkmcnt(0)
	v_ffbh_u32_e32 v178, v161
	v_min_u32_e32 v178, 32, v178
	v_lshlrev_b64 v[160:161], v178, v[160:161]
	v_min_u32_e32 v160, 1, v160
	v_or_b32_e32 v160, v161, v160
	v_cvt_f32_u32_e32 v160, v160
	v_sub_u32_e32 v178, 32, v178
	v_ldexp_f32 v160, v160, v178
	v_mul_f32_e32 v2, 0x2f800000, v160
	v_ffbh_u32_e32 v178, v163
	v_min_u32_e32 v178, 32, v178
	v_lshlrev_b64 v[162:163], v178, v[162:163]
	v_min_u32_e32 v162, 1, v162
	v_or_b32_e32 v162, v163, v162
	v_cvt_f32_u32_e32 v162, v162
	v_sub_u32_e32 v178, 32, v178
	v_ldexp_f32 v162, v162, v178
	v_mul_f32_e32 v137, 0x2f800000, v162
	v_ffbh_u32_e32 v178, v165
	v_min_u32_e32 v178, 32, v178
	v_lshlrev_b64 v[164:165], v178, v[164:165]
	v_min_u32_e32 v164, 1, v164
	v_or_b32_e32 v164, v165, v164
	v_cvt_f32_u32_e32 v164, v164
	v_sub_u32_e32 v178, 32, v178
	v_ldexp_f32 v164, v164, v178
	v_mul_f32_e32 v138, 0x2f800000, v164
	v_ffbh_u32_e32 v178, v167
	v_min_u32_e32 v178, 32, v178
	v_lshlrev_b64 v[166:167], v178, v[166:167]
	v_min_u32_e32 v166, 1, v166
	v_or_b32_e32 v166, v167, v166
	v_cvt_f32_u32_e32 v166, v166
	v_sub_u32_e32 v178, 32, v178
	v_ldexp_f32 v166, v166, v178
	v_mul_f32_e32 v139, 0x2f800000, v166
	v_ffbh_u32_e32 v178, v169
	v_min_u32_e32 v178, 32, v178
	v_lshlrev_b64 v[168:169], v178, v[168:169]
	v_min_u32_e32 v168, 1, v168
	v_or_b32_e32 v168, v169, v168
	v_cvt_f32_u32_e32 v168, v168
	v_sub_u32_e32 v178, 32, v178
	v_ldexp_f32 v168, v168, v178
	v_mul_f32_e32 v140, 0x2f800000, v168
	v_ffbh_u32_e32 v178, v171
	v_min_u32_e32 v178, 32, v178
	v_lshlrev_b64 v[170:171], v178, v[170:171]
	v_min_u32_e32 v170, 1, v170
	v_or_b32_e32 v170, v171, v170
	v_cvt_f32_u32_e32 v170, v170
	v_sub_u32_e32 v178, 32, v178
	v_ldexp_f32 v170, v170, v178
	v_mul_f32_e32 v141, 0x2f800000, v170
	v_ffbh_u32_e32 v178, v173
	v_min_u32_e32 v178, 32, v178
	v_lshlrev_b64 v[172:173], v178, v[172:173]
	v_min_u32_e32 v172, 1, v172
	v_or_b32_e32 v172, v173, v172
	v_cvt_f32_u32_e32 v172, v172
	v_sub_u32_e32 v178, 32, v178
	v_ldexp_f32 v172, v172, v178
	v_mul_f32_e32 v142, 0x2f800000, v172
	v_ffbh_u32_e32 v178, v175
	v_min_u32_e32 v178, 32, v178
	v_lshlrev_b64 v[174:175], v178, v[174:175]
	v_min_u32_e32 v174, 1, v174
	v_or_b32_e32 v174, v175, v174
	v_cvt_f32_u32_e32 v174, v174
	v_sub_u32_e32 v178, 32, v178
	v_ldexp_f32 v174, v174, v178
	v_mul_f32_e32 v135, 0x2f800000, v174

; __device__ __forceinline__ float ssq_val(u64 v) { return (float)v * (1.f / 4294967296.f); }
;     __device__ __forceinline__ void operator()(const f32x4 (&acc)[2][2][4][2], const Unit& u, int wr, int wc, int fr, int fq, LAS f32x4* rsc, bool reuse) const {
;     ...
; #pragma unroll
;                 for (int ai = 0; ai < 2; ++ai)
; #pragma unroll
;                     for (int m = 0; m < 4; ++m) rs[ai][m] = ssqf ? ssqf[row0 + ai * HALF + m * 16] : ssq_val(ssq[row0 + ai * HALF + m * 16]);
.LBB0_671:
	s_or_b64 exec, exec, s[20:21]
	s_and_b64 vcc, exec, s[48:49]
	s_cbranch_vccz .LBB0_627
	s_branch .LBB0_628
.LBB0_680:
	s_waitcnt vmcnt(0)
	v_readlane_b32 s64, v253, 14
	v_readlane_b32 s42, v252, 11
	v_readlane_b32 s44, v252, 13
	v_readlane_b32 s46, v252, 15
	v_readlane_b32 s48, v252, 17
	v_readlane_b32 s65, v253, 15
	v_readlane_b32 s69, v253, 16
	v_readlane_b32 s43, v252, 12
	v_readlane_b32 s45, v252, 14
	v_readlane_b32 s47, v252, 16
	v_readlane_b32 s49, v252, 18
	s_barrier

; __device__ __forceinline__ void gdn_local_unit(LAS unsigned char* lds, const GdnP& P, int unit, const int tid, const int pf) {
;     ...
;     else if (tid < 192) { const int t = tid - 128; const float bl = P.baf[(size_t)(row0 + t) * 16 + h], al = P.baf[(size_t)(row0 + t) * 16 + 8 + h];
;         beta[t] = 1.f / (1.f + expf(-bl)); const float x = al + P.dt_bias[h]; const float sp = x > 20.f ? x : log1pf(expf(x)); gb[t] = -expf(P.a_log[h]) * sp; }
.LBB0_888:
	s_or_b64 exec, exec, s[0:1]
	s_waitcnt lgkmcnt(0)
	s_barrier
	s_and_saveexec_b64 s[0:1], s[8:9]
	s_xor_b64 s[0:1], exec, s[0:1]
	s_cbranch_execz .LBB0_894
	s_and_saveexec_b64 s[40:41], s[10:11]
	s_cbranch_execz .LBB0_893
	v_add_u32_e32 v0, s92, v188
	s_waitcnt lgkmcnt(0)
	v_ashrrev_i32_e32 v1, 31, v0
	v_lshlrev_b64 v[0:1], 6, v[0:1]
	v_lshl_add_u64 v[0:1], s[72:73], 0, v[0:1]
	s_lshl_b32 s58, s93, 2
	v_lshl_add_u64 v[0:1], v[0:1], 0, s[58:59]
	global_load_dword v2, v[0:1], off
	s_nop 0
	global_load_dword v1, v[0:1], off offset:32
	v_mov_b32_e32 v243, s58
	global_load_dword v244, v243, s[74:75]
	global_load_dword v245, v243, s[46:47]
	s_mov_b32 s3, 0xbfb8aa3b
	s_waitcnt vmcnt(1)
	v_mul_f32_e32 v0, 0xbfb8aa3b, v2
	v_fma_f32 v3, v2, s3, -v0
	v_rndne_f32_e32 v4, v0
	v_fmac_f32_e32 v3, 0xb2a5705f, v2
	v_sub_f32_e32 v0, v0, v4
	v_add_f32_e32 v0, v0, v3
	v_exp_f32_e32 v0, v0
	v_cvt_i32_f32_e32 v3, v4
	s_mov_b32 s3, 0x42ce8ed0
	v_cmp_nlt_f32_e32 vcc, s3, v2
	s_mov_b32 s3, 0xc2b17218
	v_ldexp_f32 v0, v0, v3
	v_cndmask_b32_e32 v0, 0, v0, vcc
	v_cmp_ngt_f32_e32 vcc, s3, v2
	s_mov_b32 s3, 0x41a00000
	s_nop 0
	v_cndmask_b32_e32 v0, v214, v0, vcc
	v_add_f32_e32 v0, 1.0, v0
	v_div_scale_f32 v2, s[42:43], v0, v0, 1.0
	v_rcp_f32_e32 v3, v2
	s_nop 0
	v_fma_f32 v4, -v2, v3, 1.0
	v_fmac_f32_e32 v3, v4, v3
	v_div_scale_f32 v4, vcc, 1.0, v0, 1.0
	v_mul_f32_e32 v5, v4, v3
	v_fma_f32 v6, -v2, v5, v4
	v_fmac_f32_e32 v5, v6, v3
	v_fma_f32 v2, -v2, v5, v4
	v_div_fmas_f32 v2, v2, v3, v5
	v_div_fixup_f32 v2, v2, v0, 1.0
	v_lshl_add_u32 v0, v165, 2, v130
	ds_write_b32 v0, v2
	s_waitcnt vmcnt(0)
	v_mov_b32_e32 v2, v244
	v_add_f32_e32 v1, v1, v2
	v_cmp_nlt_f32_e32 vcc, s3, v1
	s_and_saveexec_b64 s[42:43], vcc
	s_cbranch_execz .LBB0_892
	v_mul_f32_e32 v2, 0x3fb8aa3b, v1
	v_rndne_f32_e32 v3, v2
	v_sub_f32_e32 v4, v2, v3
	v_fma_f32 v2, v1, s88, -v2
	v_fmac_f32_e32 v2, 0x32a5705f, v1
	v_add_f32_e32 v2, v4, v2
	v_cvt_i32_f32_e32 v3, v3
	v_exp_f32_e32 v2, v2
	v_cmp_ngt_f32_e32 vcc, s89, v1
	s_mov_b32 s3, 0x3f2aaaab
	v_ldexp_f32 v2, v2, v3
	v_cndmask_b32_e32 v2, 0, v2, vcc
	v_cmp_nlt_f32_e32 vcc, s90, v1
	s_nop 1
	v_cndmask_b32_e32 v1, v214, v2, vcc
	v_add_f32_e32 v4, 1.0, v1
	v_add_f32_e32 v2, -1.0, v4
	v_sub_f32_e32 v3, v2, v4
	v_add_f32_e32 v3, 1.0, v3
	v_sub_f32_e32 v2, v1, v2
	v_add_f32_e32 v5, v2, v3
	v_frexp_mant_f32_e32 v6, v4
	v_cvt_f64_f32_e32 v[2:3], v4
	v_frexp_exp_i32_f64_e32 v2, v[2:3]
	v_cmp_gt_f32_e32 vcc, s3, v6
	s_mov_b32 s3, 0x3f317218
	s_nop 0
	v_subbrev_co_u32_e32 v10, vcc, 0, v2, vcc
	v_sub_u32_e32 v2, 0, v10
	v_ldexp_f32 v3, v4, v2
	v_add_f32_e32 v4, -1.0, v3
	v_add_f32_e32 v6, 1.0, v3
	v_ldexp_f32 v2, v5, v2
	v_add_f32_e32 v5, 1.0, v4
	v_add_f32_e32 v7, -1.0, v6
	v_sub_f32_e32 v5, v3, v5
	v_sub_f32_e32 v3, v3, v7
	v_add_f32_e32 v5, v2, v5
	v_add_f32_e32 v2, v2, v3
	v_add_f32_e32 v11, v6, v2
	v_rcp_f32_e32 v13, v11
	v_sub_f32_e32 v3, v6, v11
	v_add_f32_e32 v12, v2, v3
	v_add_f32_e32 v3, v4, v5
	v_mul_f32_e32 v15, v3, v13
	v_sub_f32_e32 v2, v4, v3
	v_mul_f32_e32 v4, v11, v15
	v_fma_f32 v6, v15, v11, -v4
	v_fmac_f32_e32 v6, v15, v12
	v_add_f32_e32 v14, v5, v2
	v_add_f32_e32 v2, v4, v6
	v_sub_f32_e32 v5, v3, v2
	v_pk_add_f32 v[8:9], v[2:3], v[4:5] neg_lo:[0,1] neg_hi:[0,1]
	v_mov_b32_e32 v7, v2
	v_pk_add_f32 v[2:3], v[8:9], v[6:7] neg_lo:[0,1] neg_hi:[0,1]
	s_nop 0
	v_add_f32_e32 v3, v14, v3
	v_add_f32_e32 v2, v2, v3
	v_add_f32_e32 v3, v5, v2
	v_mul_f32_e32 v14, v13, v3
	v_mul_f32_e32 v4, v11, v14
	v_fma_f32 v6, v14, v11, -v4
	v_fmac_f32_e32 v6, v14, v12
	v_sub_f32_e32 v5, v5, v3
	v_add_f32_e32 v11, v2, v5
	v_add_f32_e32 v2, v4, v6
	v_sub_f32_e32 v5, v3, v2
	v_pk_add_f32 v[8:9], v[2:3], v[4:5] neg_lo:[0,1] neg_hi:[0,1]
	v_mov_b32_e32 v7, v2
	v_pk_add_f32 v[2:3], v[8:9], v[6:7] neg_lo:[0,1] neg_hi:[0,1]
	s_nop 0
	v_add_f32_e32 v3, v11, v3
	v_add_f32_e32 v2, v2, v3
	v_add_f32_e32 v3, v15, v14
	v_add_f32_e32 v2, v5, v2
	v_sub_f32_e32 v4, v3, v15
	v_mul_f32_e32 v2, v13, v2
	v_sub_f32_e32 v4, v14, v4
	v_add_f32_e32 v4, v4, v2
	v_add_f32_e32 v6, v3, v4
	v_mul_f32_e32 v7, v6, v6
	v_fmamk_f32 v2, v7, 0x3e9b6dac, v212
	v_fmaak_f32 v111, v7, v2, 0x3f2aaada
	v_cvt_f32_i32_e32 v2, v10
	v_sub_f32_e32 v3, v6, v3
	v_sub_f32_e32 v3, v4, v3
	v_ldexp_f32 v8, v3, 1
	v_mul_f32_e32 v3, v6, v7
	v_ldexp_f32 v5, v6, 1
	v_pk_mul_f32 v[6:7], v[2:3], v[110:111]
	s_nop 0
	v_fma_f32 v4, v2, s3, -v6
	v_fmac_f32_e32 v4, 0xb102e308, v2
	v_pk_add_f32 v[2:3], v[6:7], v[4:5]
	s_mov_b32 s3, 0x7f800000
	v_sub_f32_e32 v5, v3, v5
	v_sub_f32_e32 v5, v7, v5
	v_add_f32_e32 v9, v8, v5
	v_mov_b32_e32 v8, v6
	v_pk_add_f32 v[6:7], v[2:3], v[6:7] neg_lo:[0,1] neg_hi:[0,1]
	v_pk_add_f32 v[10:11], v[2:3], v[8:9]
	v_mov_b32_e32 v5, v2
	v_mov_b32_e32 v7, v11
	v_pk_add_f32 v[12:13], v[4:5], v[6:7] neg_lo:[0,1] neg_hi:[0,1]
	v_pk_add_f32 v[4:5], v[4:5], v[6:7]
	v_mov_b32_e32 v8, v9
	v_pk_add_f32 v[6:7], v[4:5], v[2:3] op_sel:[1,0] op_sel_hi:[0,1] neg_lo:[0,1] neg_hi:[0,1]
	v_pk_add_f32 v[14:15], v[10:11], v[6:7] op_sel_hi:[1,0] neg_lo:[0,1] neg_hi:[0,1]
	v_mov_b32_e32 v10, v11
	v_mov_b32_e32 v11, v5
	v_pk_mov_b32 v[6:7], v[2:3], v[6:7] op_sel:[1,0]
	v_mov_b32_e32 v9, v2
	v_pk_add_f32 v[6:7], v[10:11], v[6:7] neg_lo:[0,1] neg_hi:[0,1]
	v_mov_b32_e32 v14, v12
	v_pk_add_f32 v[2:3], v[8:9], v[6:7] neg_lo:[0,1] neg_hi:[0,1]
	v_mov_b32_e32 v13, v5
	v_pk_add_f32 v[6:7], v[14:15], v[2:3]
	v_cmp_neq_f32_e32 vcc, s3, v1
	v_pk_add_f32 v[8:9], v[6:7], v[6:7] op_sel:[0,1] op_sel_hi:[1,0]
	s_mov_b32 s3, 0x33800000
	v_pk_add_f32 v[4:5], v[4:5], v[8:9] op_sel:[1,0] op_sel_hi:[0,1]
	v_mov_b32_e32 v7, v4
	v_pk_add_f32 v[10:11], v[6:7], v[12:13] neg_lo:[0,1] neg_hi:[0,1]
	v_mov_b32_e32 v3, v8
	v_sub_f32_e32 v5, v6, v10
	v_pk_add_f32 v[2:3], v[2:3], v[10:11] neg_lo:[0,1] neg_hi:[0,1]
	v_sub_f32_e32 v5, v12, v5
	v_add_f32_e32 v2, v2, v5
	v_add_f32_e32 v2, v2, v3
	v_add_f32_e32 v2, v4, v2
	v_cndmask_b32_e32 v2, v214, v2, vcc
	v_cmp_lt_f32_e64 vcc, |v1|, s3
	s_nop 1
	v_cndmask_b32_e32 v1, v2, v1, vcc
.LBB0_892:
	s_or_b64 exec, exec, s[42:43]
	v_mov_b32_e32 v2, v245
	v_mul_f32_e32 v3, 0x3fb8aa3b, v2
	v_fma_f32 v4, v2, s88, -v3
	v_rndne_f32_e32 v5, v3
	v_fmac_f32_e32 v4, 0x32a5705f, v2
	v_sub_f32_e32 v3, v3, v5
	v_add_f32_e32 v3, v3, v4
	v_cvt_i32_f32_e32 v5, v5
	v_exp_f32_e32 v3, v3
	v_cmp_ngt_f32_e32 vcc, s89, v2
	v_ldexp_f32 v3, v3, v5
	s_nop 0
	v_cndmask_b32_e32 v3, 0, v3, vcc
	v_cmp_nlt_f32_e32 vcc, s90, v2
	s_nop 1
	v_cndmask_b32_e32 v2, v214, v3, vcc
	v_mul_f32_e64 v1, v1, -v2
	ds_write_b32 v0, v1 offset:768

; #define LAS __attribute__((address_space(3)))
; template <bool MOBA>
; __device__ __forceinline__ void attn_unit(LAS unsigned char* lds, const bf16_t* Qp, int ldq, const bf16_t* Kp, const bf16_t* Vp, int ldkv, bf16_t* Op, int ldo, int qt, const float* kmean, const float* relb, const int tid) {
;     ...
;         if (tid < 128) { unsigned mask = 0u;
;             if (own <= 3) mask = (1u << own) - 1u;
;             else { const LAS float* sc = (const LAS float*)(lds + AT_SC) + tid * 16;
;                 for (int r = 0; r < 3; ++r) { float best = -INFINITY; int bi = 0; for (int j = 0; j < own; ++j) { const float v = sc[j]; if (!((mask >> j) & 1u) && v > best) { best = v; bi = j; } } mask |= 1u << bi; } }
;             ((LAS unsigned*)(lds + AT_SEL))[tid] = mask; }
;     ...
;     for (int i = 0; i < 4; ++i) { const int id = tid + 512 * i, r = id >> 4, c = id & 15; kreg[i] = *(const u32x4*)(Kp + (size_t)r * ldkv + c * 8); vreg[i] = *(const u32x4*)(Vp + (size_t)r * ldkv + c * 8); }
.LBB0_1163:
	s_or_b64 exec, exec, s[8:9]
	s_waitcnt lgkmcnt(0)
	s_barrier
	v_mov_b32_e32 v139, v115
	v_lshl_add_u64 v[0:1], s[28:29], 0, v[138:139]
	v_lshl_add_u64 v[2:3], v[0:1], 0, s[22:23]
	v_lshl_add_u64 v[4:5], v[0:1], 0, v[140:141]
	v_lshl_add_u64 v[6:7], v[2:3], 0, v[140:141]
	global_load_dwordx4 v[32:35], v[4:5], off offset:2048
	global_load_dwordx4 v[36:39], v[6:7], off
	v_lshl_add_u64 v[4:5], v[0:1], 0, v[142:143]
	v_lshl_add_u64 v[6:7], v[2:3], 0, v[142:143]
	global_load_dwordx4 v[40:43], v[4:5], off offset:2048
	global_load_dwordx4 v[44:47], v[6:7], off
	v_lshl_add_u64 v[4:5], v[0:1], 0, v[144:145]
	v_lshl_add_u64 v[0:1], v[0:1], 0, v[146:147]
	v_lshl_add_u64 v[6:7], v[2:3], 0, v[144:145]
	global_load_dwordx4 v[52:55], v[4:5], off offset:2048
	global_load_dwordx4 v[68:71], v[6:7], off
	v_lshl_add_u64 v[2:3], v[2:3], 0, v[146:147]
	global_load_dwordx4 v[72:75], v[0:1], off offset:2048
	global_load_dwordx4 v[76:79], v[2:3], off
	s_and_saveexec_b64 s[30:31], s[6:7]
	s_cbranch_execz .LBB0_1175
	s_cmp_lt_u32 s53, 8
	s_mov_b64 s[8:9], -1
	s_cbranch_scc1 .LBB0_1172
	v_mov_b32_e32 v0, 0
	v_mov_b32_e32 v1, 0xff800000
	s_mov_b32 s8, 0
	v_mov_b32_e32 v2, v188

; #define LAS __attribute__((address_space(3)))
; template <bool MOBA>
; __device__ __forceinline__ void attn_unit(LAS unsigned char* lds, const bf16_t* Qp, int ldq, const bf16_t* Kp, const bf16_t* Vp, int ldkv, bf16_t* Op, int ldo, int qt, const float* kmean, const float* relb, const int tid) {
;     ...
; #pragma unroll
;         for (int s = 0; s < 4; ++s) qf[s] = *(const LAS bf16x8*)(lds + AT_KS + (w * 16 + l15) * AT_PITCH + (quad * 8 + 32 * s) * 2);
;         mysel = ((LAS unsigned*)(lds + AT_SEL))[w * 16 + l15];
;         { unsigned m = mysel; m |= __shfl_xor(m, 1); m |= __shfl_xor(m, 2); m |= __shfl_xor(m, 4); m |= __shfl_xor(m, 8); wave_mask = __builtin_amdgcn_readfirstlane(m); }
;     } else {
; #pragma unroll
;         for (int s = 0; s < 4; ++s) qf[s] = *(const bf16x8*)(Qp + (size_t)(w * 16 + l15) * ldq + quad * 8 + 32 * s);
;     }
;     f32x4 oacc[8]; float mrow = -INFINITY, lrow = 0.f;
; #pragma unroll
;     for (int n = 0; n < 8; ++n) oacc[n] = (f32x4){0.f, 0.f, 0.f, 0.f};
;     const int nhalf = MOBA ? own * 2 + (qt & 1) + 1 : 2;
;     const float sc2 = 0.08838834764831845f * L2E;
;     u32x4 kreg[4], vreg[4];
; #pragma unroll
;     for (int i = 0; i < 4; ++i) { const int id = tid + 512 * i, r = id >> 4, c = id & 15; kreg[i] = *(const u32x4*)(Kp + (size_t)r * ldkv + c * 8); vreg[i] = *(const u32x4*)(Vp + (size_t)r * ldkv + c * 8); }
.LBB0_1175:
	s_or_b64 exec, exec, s[30:31]
	s_waitcnt lgkmcnt(0)
	s_barrier
	s_ashr_i32 s8, s55, 2
	s_and_b32 s28, s8, -16
	v_or_b32_e32 v139, s28, v170
	v_lshl_add_u32 v0, v139, 2, 0
	v_add_u32_e32 v0, 0x15800, v0
	ds_read_b32 v149, v0
	v_and_b32_e32 v1, 64, v195
	v_xor_b32_e32 v0, 1, v195
	v_add_u32_e32 v2, 64, v1
	v_cmp_lt_i32_e32 vcc, v0, v2
	v_xor_b32_e32 v1, 2, v195
	s_lshl_b32 s36, s53, 7
	v_cndmask_b32_e32 v0, v195, v0, vcc
	v_lshlrev_b32_e32 v0, 2, v0
	s_waitcnt lgkmcnt(0)
	ds_bpermute_b32 v0, v0, v149
	v_cmp_lt_i32_e32 vcc, v1, v2
	v_mov_b32_e32 v82, v115
	v_mov_b32_e32 v83, v115
	v_cndmask_b32_e32 v1, v195, v1, vcc
	s_waitcnt lgkmcnt(0)
	v_or_b32_e32 v0, v0, v149
	v_lshlrev_b32_e32 v1, 2, v1
	ds_bpermute_b32 v1, v1, v0
	s_add_i32 s37, s36, s28
	v_mov_b32_e32 v80, v115
	v_mov_b32_e32 v81, v115
	v_mov_b64_e32 v[86:87], v[82:83]
	s_waitcnt lgkmcnt(0)
	v_or_b32_e32 v3, v0, v1
	v_xor_b32_e32 v0, 4, v195
	v_cmp_lt_i32_e32 vcc, v0, v2
	v_mov_b64_e32 v[90:91], v[82:83]
	v_mov_b64_e32 v[94:95], v[82:83]
	v_cndmask_b32_e32 v0, v195, v0, vcc
	v_lshlrev_b32_e32 v0, 2, v0
	ds_bpermute_b32 v4, v0, v3
	v_mad_u64_u32 v[0:1], s[8:9], v139, s41, v[126:127]
	ds_read_b128 v[48:51], v0
	ds_read_b128 v[56:59], v0 offset:64
	ds_read_b128 v[60:63], v0 offset:128
	ds_read_b128 v[64:67], v0 offset:192
	v_mov_b64_e32 v[98:99], v[82:83]
	s_waitcnt lgkmcnt(4)
	v_or_b32_e32 v1, v3, v4
	v_xor_b32_e32 v3, 8, v195
	v_cmp_lt_i32_e32 vcc, v3, v2
	v_mov_b64_e32 v[102:103], v[82:83]
	v_mov_b64_e32 v[106:107], v[82:83]
	v_cndmask_b32_e32 v3, v195, v3, vcc
	v_lshlrev_b32_e32 v3, 2, v3
	ds_bpermute_b32 v3, v3, v1
	v_mov_b64_e32 v[110:111], v[82:83]
	s_mov_b32 s34, 0
	v_lshl_add_u64 v[158:159], v[150:151], 0, s[10:11]
	v_lshl_add_u64 v[160:161], v[152:153], 0, s[10:11]
	s_waitcnt lgkmcnt(0)
	v_or_b32_e32 v0, v1, v3
	v_lshl_add_u64 v[162:163], v[154:155], 0, s[10:11]
	v_readfirstlane_b32 s35, v0
	v_xor_b32_e32 v0, 16, v195
	v_cmp_lt_i32_e32 vcc, v0, v2
	v_lshl_add_u64 v[164:165], v[156:157], 0, s[10:11]
	v_add_u32_e32 v199, s37, v189
	v_cndmask_b32_e32 v0, v195, v0, vcc
	v_lshlrev_b32_e32 v197, 2, v0
	v_xor_b32_e32 v0, 32, v195
	v_cmp_lt_i32_e32 vcc, v0, v2
	v_mov_b32_e32 v201, 0xff800000
	v_mov_b32_e32 v200, 0
	v_cndmask_b32_e32 v0, v195, v0, vcc
	v_lshlrev_b32_e32 v198, 2, v0
	v_mov_b64_e32 v[84:85], v[80:81]
	v_mov_b64_e32 v[88:89], v[80:81]
	v_mov_b64_e32 v[92:93], v[80:81]
	v_mov_b64_e32 v[96:97], v[80:81]
	v_mov_b64_e32 v[100:101], v[80:81]
	v_mov_b64_e32 v[104:105], v[80:81]
	v_mov_b64_e32 v[108:109], v[80:81]
	s_mov_b32 s38, 0

; __device__ __forceinline__ u64 ssq_fix(float v) { return (u64)(v * 4294967296.f); }
; __device__ __forceinline__ float ssq_val(u64 v) { return (float)v * (1.f / 4294967296.f); }
;     __device__ __forceinline__ void operator()(const f32x4 (&acc)[2][2][4][2], const Unit& u, int wr, int wc, int fr, int fq, LAS f32x4* rsc, bool reuse) const {
;     ...
; #pragma unroll
;                 for (int ai = 0; ai < 2; ++ai)
; #pragma unroll
;                     for (int m = 0; m < 4; ++m) rs[ai][m] = ssqf ? ssqf[row0 + ai * HALF + m * 16] : ssq_val(ssq[row0 + ai * HALF + m * 16]);
.LBB0_1591:
	s_and_b64 vcc, exec, s[38:39]
	s_cbranch_vccz .LBB0_1631
	s_cmp_eq_u32 s4, s41
	s_mov_b64 s[0:1], -1
	s_cbranch_scc1 .LBB0_1618
	v_ashrrev_i32_e32 v211, 31, v210
	s_cmp_lg_u64 s[78:79], 0
	s_cbranch_scc0 .Lrs2_u64
	v_lshl_add_u64 v[176:177], v[210:211], 2, s[78:79]
	flat_load_dword v0, v[176:177]
	flat_load_dword v135, v[176:177] offset:64
	flat_load_dword v136, v[176:177] offset:128
	flat_load_dword v137, v[176:177] offset:192
	flat_load_dword v138, v[176:177] offset:512
	flat_load_dword v139, v[176:177] offset:576
	flat_load_dword v140, v[176:177] offset:640
	flat_load_dword v133, v[176:177] offset:704
	s_waitcnt vmcnt(0) lgkmcnt(0)
	s_branch .LBB0_1617
.Lrs2_u64:
	v_lshl_add_u64 v[176:177], v[210:211], 3, s[52:53]
	flat_load_dwordx2 v[160:161], v[176:177]
	flat_load_dwordx2 v[162:163], v[176:177] offset:128
	flat_load_dwordx2 v[164:165], v[176:177] offset:256
	flat_load_dwordx2 v[166:167], v[176:177] offset:384
	flat_load_dwordx2 v[168:169], v[176:177] offset:1024
	flat_load_dwordx2 v[170:171], v[176:177] offset:1152
	flat_load_dwordx2 v[172:173], v[176:177] offset:1280
	flat_load_dwordx2 v[174:175], v[176:177] offset:1408
	s_waitcnt vmcnt(0) lgkmcnt(0)
	v_ffbh_u32_e32 v178, v161
	v_min_u32_e32 v178, 32, v178
	v_lshlrev_b64 v[160:161], v178, v[160:161]
	v_min_u32_e32 v160, 1, v160
	v_or_b32_e32 v160, v161, v160
	v_cvt_f32_u32_e32 v160, v160
	v_sub_u32_e32 v178, 32, v178
	v_ldexp_f32 v160, v160, v178
	v_mul_f32_e32 v0, 0x2f800000, v160
	v_ffbh_u32_e32 v178, v163
	v_min_u32_e32 v178, 32, v178
	v_lshlrev_b64 v[162:163], v178, v[162:163]
	v_min_u32_e32 v162, 1, v162
	v_or_b32_e32 v162, v163, v162
	v_cvt_f32_u32_e32 v162, v162
	v_sub_u32_e32 v178, 32, v178
	v_ldexp_f32 v162, v162, v178
	v_mul_f32_e32 v135, 0x2f800000, v162
	v_ffbh_u32_e32 v178, v165
	v_min_u32_e32 v178, 32, v178
	v_lshlrev_b64 v[164:165], v178, v[164:165]
	v_min_u32_e32 v164, 1, v164
	v_or_b32_e32 v164, v165, v164
	v_cvt_f32_u32_e32 v164, v164
	v_sub_u32_e32 v178, 32, v178
	v_ldexp_f32 v164, v164, v178
	v_mul_f32_e32 v136, 0x2f800000, v164
	v_ffbh_u32_e32 v178, v167
	v_min_u32_e32 v178, 32, v178
	v_lshlrev_b64 v[166:167], v178, v[166:167]
	v_min_u32_e32 v166, 1, v166
	v_or_b32_e32 v166, v167, v166
	v_cvt_f32_u32_e32 v166, v166
	v_sub_u32_e32 v178, 32, v178
	v_ldexp_f32 v166, v166, v178
	v_mul_f32_e32 v137, 0x2f800000, v166
	v_ffbh_u32_e32 v178, v169
	v_min_u32_e32 v178, 32, v178
	v_lshlrev_b64 v[168:169], v178, v[168:169]
	v_min_u32_e32 v168, 1, v168
	v_or_b32_e32 v168, v169, v168
	v_cvt_f32_u32_e32 v168, v168
	v_sub_u32_e32 v178, 32, v178
	v_ldexp_f32 v168, v168, v178
	v_mul_f32_e32 v138, 0x2f800000, v168
	v_ffbh_u32_e32 v178, v171
	v_min_u32_e32 v178, 32, v178
	v_lshlrev_b64 v[170:171], v178, v[170:171]
	v_min_u32_e32 v170, 1, v170
	v_or_b32_e32 v170, v171, v170
	v_cvt_f32_u32_e32 v170, v170
	v_sub_u32_e32 v178, 32, v178
	v_ldexp_f32 v170, v170, v178
	v_mul_f32_e32 v139, 0x2f800000, v170
	v_ffbh_u32_e32 v178, v173
	v_min_u32_e32 v178, 32, v178
	v_lshlrev_b64 v[172:173], v178, v[172:173]
	v_min_u32_e32 v172, 1, v172
	v_or_b32_e32 v172, v173, v172
	v_cvt_f32_u32_e32 v172, v172
	v_sub_u32_e32 v178, 32, v178
	v_ldexp_f32 v172, v172, v178
	v_mul_f32_e32 v140, 0x2f800000, v172
	v_ffbh_u32_e32 v178, v175
	v_min_u32_e32 v178, 32, v178
	v_lshlrev_b64 v[174:175], v178, v[174:175]
	v_min_u32_e32 v174, 1, v174
	v_or_b32_e32 v174, v175, v174
	v_cvt_f32_u32_e32 v174, v174
	v_sub_u32_e32 v178, 32, v178
	v_ldexp_f32 v174, v174, v178
	v_mul_f32_e32 v133, 0x2f800000, v174

; __device__ __forceinline__ void gemm_range(const Args& a, LAS unsigned char* lds, int lo, int hi, int first, int last, int G, int bx, int NGW, const XcdBarrier& xbar) {
;     ...
;             switch (ph) {
;             case P_GU1: g = {hb, (const bf16_t*)(ws + WS_WGU), TOK, NGU, DM, DM}; E.mode = pg8::E_GU; E.ssq = ssqx; E.outb = hff; E.ldo = FF; break;
;             case P_DOWN1: g = {hff, (const bf16_t*)(ws + WS_WD), TOK, DM, FF, FF}; E.mode = pg8::E_RESID; E.hinb = hb; E.hout = nullptr; E.alpha = 0.5f; E.ssq_out = ssqx + TOK; E.hb = hb; break;
;             case P_PROJ: g = {hb, (const bf16_t*)(ws + WS_WIN), TOK, NIN, DM, DM}; E.mode = pg8::E_SCALE; E.ssq = ssqx + TOK; E.outb = proj; E.ldo = NIN; E.halo = (bf16_t*)(ws + WS_HALO); E.baf = (float*)(ws + WS_BAF); break;
;             case P_BRANCH:
;                 if (gi == 0) { g = {proj, (const bf16_t*)(ws + WS_WBA), TOK, DM, 1024, NIN}; E.mode = pg8::E_BR1; }
;                 else { g = {proj + C_Z, (const bf16_t*)(ws + WS_WBD), TOK, DM, 1024, NIN}; E.mode = pg8::E_BR2; E.gate = proj + C_GB; }
;                 E.outb = proj + C_GA; E.ldo = NIN; break;
;             case P_WOUT: g = {proj + C_GA, (const bf16_t*)(ws + WS_WOUT), TOK, DM, DM, NIN}; E.mode = pg8::E_RESID; E.hinb = hb; E.hout = nullptr; E.alpha = 1.f; E.ssq_out = ssqx + 2 * TOK; E.hb = hb; break;
;             case P_XQ:
;                 if (gi == 0) { g = {hb, (const bf16_t*)(ws + WS_WQ), TOK, 512, DM, DM}; E.ssq = ssqx + 2 * TOK; E.outb = (bf16_t*)(ws + WS_QX); E.ldo = 512; }
;                 else { g = {(const bf16_t*)(ws + WS_MEMB), (const bf16_t*)(ws + WS_WKV), 1024, 1024, DM, DM}; E.ssqf = ctl + CT_SSQM; E.outb = (bf16_t*)(ws + WS_KVX); E.ldo = 1024; rot = 128; }
;                 E.mode = pg8::E_SCALE; break;
;             case P_XO: g = {(const bf16_t*)(ws + WS_OX), (const bf16_t*)(ws + WS_WO), TOK, DM, 512, 512}; E.mode = pg8::E_RESID; E.hinb = hb; E.hout = nullptr; E.alpha = 1.f; E.ssq_out = ssqx + 3 * TOK; E.hb = hb; break;
;             case P_GU2: g = {hb, (const bf16_t*)(ws + WS_WGU), TOK, NGU, DM, DM}; E.mode = pg8::E_GU; E.ssq = ssqx + 3 * TOK; E.outb = hff; E.ldo = FF; break;
;             default: g = {hff, (const bf16_t*)(ws + WS_WD), TOK, DM, FF, FF}; E.mode = pg8::E_RESID; E.hinb = hb; E.hout = nullptr; E.alpha = 0.5f; E.ssq_out = ssqx + 4 * TOK; E.hb = hb; break;
;             }
.LBB0_1634:
	s_cbranch_execnz .LBB0_1630
	s_branch .LBB0_1631
.LBB0_1643:
	v_readlane_b32 s96, v253, 18
	v_readlane_b32 s90, v253, 30
	v_readlane_b32 s34, v253, 28
	s_mov_b32 s8, 1.0
	s_mov_b32 s6, 0
	s_mov_b32 s7, 1
	s_movk_i32 s5, 0x2d00
	s_mov_b32 s58, 64
	v_readlane_b32 s97, v253, 19
	v_readlane_b32 s91, v253, 31
	s_mov_b32 s3, s21
	s_mov_b64 s[24:25], 0
	s_mov_b64 s[30:31], 0
	s_mov_b64 s[26:27], 0
	v_readlane_b32 s35, v253, 29
	s_mov_b64 s[0:1], s[40:41]
	s_mov_b32 s2, 0
	s_and_b64 vcc, exec, s[36:37]
	s_cbranch_vccnz .LBB0_1414

; __device__ __forceinline__ u64 ssq_fix(float v) { return (u64)(v * 4294967296.f); }
; __device__ __forceinline__ float ssq_val(u64 v) { return (float)v * (1.f / 4294967296.f); }
;     __device__ __forceinline__ void operator()(const f32x4 (&acc)[2][2][4][2], const Unit& u, int wr, int wc, int fr, int fq, LAS f32x4* rsc, bool reuse) const {
;     ...
; #pragma unroll
;                 for (int ai = 0; ai < 2; ++ai)
; #pragma unroll
;                     for (int m = 0; m < 4; ++m) rs[ai][m] = ssqf ? ssqf[row0 + ai * HALF + m * 16] : ssq_val(ssq[row0 + ai * HALF + m * 16]);
.LBB0_2003:
	s_and_b64 vcc, exec, s[50:51]
	s_cbranch_vccz .LBB0_2081
	s_mov_b64 s[0:1], -1
	s_cmp_eq_u32 s2, s73
	v_ashrrev_i32_e32 v211, 31, v210
	s_cbranch_scc1 .LBB0_2084
	s_cmp_lg_u64 s[64:65], 0
	s_cbranch_scc0 .Lrs3_u64
	v_lshl_add_u64 v[176:177], v[210:211], 2, s[64:65]
	flat_load_dword v2, v[176:177]
	flat_load_dword v137, v[176:177] offset:64
	flat_load_dword v138, v[176:177] offset:128
	flat_load_dword v139, v[176:177] offset:192
	flat_load_dword v140, v[176:177] offset:512
	flat_load_dword v141, v[176:177] offset:576
	flat_load_dword v142, v[176:177] offset:640
	flat_load_dword v135, v[176:177] offset:704
	s_waitcnt vmcnt(0) lgkmcnt(0)
	s_branch .LBB0_2029
.Lrs3_u64:
	v_lshl_add_u64 v[176:177], v[210:211], 3, s[16:17]
	flat_load_dwordx2 v[160:161], v[176:177]
	flat_load_dwordx2 v[162:163], v[176:177] offset:128
	flat_load_dwordx2 v[164:165], v[176:177] offset:256
	flat_load_dwordx2 v[166:167], v[176:177] offset:384
	flat_load_dwordx2 v[168:169], v[176:177] offset:1024
	flat_load_dwordx2 v[170:171], v[176:177] offset:1152
	flat_load_dwordx2 v[172:173], v[176:177] offset:1280
	flat_load_dwordx2 v[174:175], v[176:177] offset:1408
	s_waitcnt vmcnt(0) lgkmcnt(0)
	v_ffbh_u32_e32 v178, v161
	v_min_u32_e32 v178, 32, v178
	v_lshlrev_b64 v[160:161], v178, v[160:161]
	v_min_u32_e32 v160, 1, v160
	v_or_b32_e32 v160, v161, v160
	v_cvt_f32_u32_e32 v160, v160
	v_sub_u32_e32 v178, 32, v178
	v_ldexp_f32 v160, v160, v178
	v_mul_f32_e32 v2, 0x2f800000, v160
	v_ffbh_u32_e32 v178, v163
	v_min_u32_e32 v178, 32, v178
	v_lshlrev_b64 v[162:163], v178, v[162:163]
	v_min_u32_e32 v162, 1, v162
	v_or_b32_e32 v162, v163, v162
	v_cvt_f32_u32_e32 v162, v162
	v_sub_u32_e32 v178, 32, v178
	v_ldexp_f32 v162, v162, v178
	v_mul_f32_e32 v137, 0x2f800000, v162
	v_ffbh_u32_e32 v178, v165
	v_min_u32_e32 v178, 32, v178
	v_lshlrev_b64 v[164:165], v178, v[164:165]
	v_min_u32_e32 v164, 1, v164
	v_or_b32_e32 v164, v165, v164
	v_cvt_f32_u32_e32 v164, v164
	v_sub_u32_e32 v178, 32, v178
	v_ldexp_f32 v164, v164, v178
	v_mul_f32_e32 v138, 0x2f800000, v164
	v_ffbh_u32_e32 v178, v167
	v_min_u32_e32 v178, 32, v178
	v_lshlrev_b64 v[166:167], v178, v[166:167]
	v_min_u32_e32 v166, 1, v166
	v_or_b32_e32 v166, v167, v166
	v_cvt_f32_u32_e32 v166, v166
	v_sub_u32_e32 v178, 32, v178
	v_ldexp_f32 v166, v166, v178
	v_mul_f32_e32 v139, 0x2f800000, v166
	v_ffbh_u32_e32 v178, v169
	v_min_u32_e32 v178, 32, v178
	v_lshlrev_b64 v[168:169], v178, v[168:169]
	v_min_u32_e32 v168, 1, v168
	v_or_b32_e32 v168, v169, v168
	v_cvt_f32_u32_e32 v168, v168
	v_sub_u32_e32 v178, 32, v178
	v_ldexp_f32 v168, v168, v178
	v_mul_f32_e32 v140, 0x2f800000, v168
	v_ffbh_u32_e32 v178, v171
	v_min_u32_e32 v178, 32, v178
	v_lshlrev_b64 v[170:171], v178, v[170:171]
	v_min_u32_e32 v170, 1, v170
	v_or_b32_e32 v170, v171, v170
	v_cvt_f32_u32_e32 v170, v170
	v_sub_u32_e32 v178, 32, v178
	v_ldexp_f32 v170, v170, v178
	v_mul_f32_e32 v141, 0x2f800000, v170
	v_ffbh_u32_e32 v178, v173
	v_min_u32_e32 v178, 32, v178
	v_lshlrev_b64 v[172:173], v178, v[172:173]
	v_min_u32_e32 v172, 1, v172
	v_or_b32_e32 v172, v173, v172
	v_cvt_f32_u32_e32 v172, v172
	v_sub_u32_e32 v178, 32, v178
	v_ldexp_f32 v172, v172, v178
	v_mul_f32_e32 v142, 0x2f800000, v172
	v_ffbh_u32_e32 v178, v175
	v_min_u32_e32 v178, 32, v178
	v_lshlrev_b64 v[174:175], v178, v[174:175]
	v_min_u32_e32 v174, 1, v174
	v_or_b32_e32 v174, v175, v174
	v_cvt_f32_u32_e32 v174, v174
	v_sub_u32_e32 v178, 32, v178
	v_ldexp_f32 v174, v174, v178
	v_mul_f32_e32 v135, 0x2f800000, v174

; __device__ __forceinline__ float ssq_val(u64 v) { return (float)v * (1.f / 4294967296.f); }
; #define PG8_WAIT_V(n) asm volatile("s_waitcnt vmcnt(" #n ")" ::: "memory")
; #define PG8_BAR __builtin_amdgcn_s_barrier()
;     __device__ __forceinline__ void operator()(const f32x4 (&acc)[2][2][4][2], const Unit& u, int wr, int wc, int fr, int fq, LAS f32x4* rsc, bool reuse) const {
;     ...
;                 for (int ai = 0; ai < 2; ++ai)
; #pragma unroll
;                     for (int m = 0; m < 4; ++m) rs[ai][m] = ssqf ? ssqf[row0 + ai * HALF + m * 16] : ssq_val(ssq[row0 + ai * HALF + m * 16]);
; __device__ __forceinline__ void gemm_phase(LAS unsigned char* lds, const Gemm g, const StaticOrder& S, const LAS Epi* Ep, const int tid) {
;     ...
;     PG8_WAIT_V(0);
;     PG8_BAR;
.LBB0_2110:
	s_or_b64 exec, exec, s[16:17]
	s_and_b64 vcc, exec, s[48:49]
	s_cbranch_vccz .LBB0_2066
	s_branch .LBB0_2067
.LBB0_2119:
	s_waitcnt vmcnt(0)
	v_readlane_b32 s64, v253, 14
	v_readlane_b32 s24, v252, 11
	v_readlane_b32 s65, v253, 15
	v_readlane_b32 s69, v253, 16
	v_readlane_b32 s25, v252, 12
	s_barrier
